# SwiGLU epilogue + MLA two-tile compute blocks rewritten (sequential per tile, 2-chain row max, deeper LDS fragment prefetch)
# baseline (speedup 1.0000x reference)
; template <int DQK, int DV, int MODE, int QPRE, bool DIFF> ...
;     ...
;             if (!QKFIRST) {
;                 const LAS unsigned char* kb = lds + bi * BUF + l32 * KST + hi * 16;
;             {
;                 const bf16x8 a0 = *(const LAS bf16x8*)(kb), a1 = *(const LAS bf16x8*)(kb + 32 * KST);
;                 if (MODE == 1) { const f32x16 z16 = {0.f, 0.f, 0.f, 0.f, 0.f, 0.f, 0.f, 0.f, 0.f, 0.f, 0.f, 0.f, 0.f, 0.f, 0.f, 0.f};
;                     s0 = __builtin_amdgcn_mfma_f32_32x32x16_bf16(a0, qf[0], z16, 0, 0, 0); s1 = __builtin_amdgcn_mfma_f32_32x32x16_bf16(a1, qf[0], z16, 0, 0, 0); }
;                 else { s0 = __builtin_amdgcn_mfma_f32_32x32x16_bf16(a0, qf[0], negm, 0, 0, 0); s1 = __builtin_amdgcn_mfma_f32_32x32x16_bf16(a1, qf[0], negm, 0, 0, 0); }
;             }
; #pragma unroll
;             for (int d0 = 1; d0 < ND0; ++d0) {
;                 const bf16x8 a0 = *(const LAS bf16x8*)(kb + d0 * 32), a1 = *(const LAS bf16x8*)(kb + 32 * KST + d0 * 32);
;                 s0 = __builtin_amdgcn_mfma_f32_32x32x16_bf16(a0, qf[d0], s0, 0, 0, 0);
;                 s1 = __builtin_amdgcn_mfma_f32_32x32x16_bf16(a1, qf[d0], s1, 0, 0, 0);
;             }
;             }
;             bf16x8 vf[2][4];
;     ...
;             ATT_LOADV(vf[0], 0); if (!DEEP) ATT_LOADV(vf[1], 1);
;             __builtin_amdgcn_sched_barrier(0);
;             if (MODE != 1) {
;                 float mx = fmaxf(s0[0], s1[0]);
; #pragma unroll
;                 for (int r = 1; r < 16; ++r) mx = fmaxf(fmaxf(mx, s0[r]), s1[r]);
;                 { float a, b; swap32(mx, a, b); mx = fmaxf(a, b); }
;                 const bool first = (i == 0);
;                 if (first || __any(mx > 8.0f)) {
;                     const float dl = first ? mx : fmaxf(mx, 0.f);
;                     mhat += dl;
; #pragma unroll
;                     for (int r = 0; r < 16; ++r) { s0[r] -= dl; s1[r] -= dl; negm[r] = -mhat; }
;                     if (DEEP && QKFIRST && hf == 0 && (ATT_TILE(i0 + UNR - 1) <= my_last)) {
; #pragma unroll
;                         for (int r = 0; r < 16; ++r) { sq[UNR - 1][0][r] -= dl; sq[UNR - 1][1][r] -= dl; }
;                     }
;                     if (!first) {
;                         const float alpha = __builtin_amdgcn_exp2f(-dl);
;                         l_run *= alpha;
; #pragma unroll
;                         for (int i2 = 0; i2 < NDB; ++i2)
; #pragma unroll
.Lmla_pair0:
	ds_read_b128 v[152:155], v195
	ds_read_b128 v[156:159], v195 offset:6656
	ds_read_b128 v[160:163], v195 offset:32
	ds_read_b128 v[164:167], v195 offset:6688
	ds_read_b128 v[236:239], v195 offset:64
	ds_read_b128 v[240:243], v195 offset:6720
	s_waitcnt lgkmcnt(5)
	v_mfma_f32_32x32x16_bf16 v[48:63], v[152:155], v[128:131], v[32:47]
	ds_read_b128 v[244:247], v195 offset:96
	s_waitcnt lgkmcnt(5)
	v_mfma_f32_32x32x16_bf16 v[64:79], v[156:159], v[128:131], v[32:47]
	ds_read_b128 v[248:251], v195 offset:6752
	s_waitcnt lgkmcnt(5)
	v_mfma_f32_32x32x16_bf16 v[48:63], v[160:163], v[132:135], v[48:63]
	ds_read_b128 v[152:155], v195 offset:128
	s_waitcnt lgkmcnt(5)
	v_mfma_f32_32x32x16_bf16 v[64:79], v[164:167], v[132:135], v[64:79]
	ds_read_b128 v[156:159], v195 offset:6784
	s_waitcnt lgkmcnt(5)
	v_mfma_f32_32x32x16_bf16 v[48:63], v[236:239], v[136:139], v[48:63]
	ds_read_b128 v[160:163], v195 offset:160
	s_waitcnt lgkmcnt(5)
	v_mfma_f32_32x32x16_bf16 v[64:79], v[240:243], v[136:139], v[64:79]
	ds_read_b128 v[164:167], v195 offset:6816
	s_waitcnt lgkmcnt(5)
	v_mfma_f32_32x32x16_bf16 v[48:63], v[244:247], v[140:143], v[48:63]
	ds_read_b128 v[236:239], v198 offset:13312
	s_waitcnt lgkmcnt(5)
	v_mfma_f32_32x32x16_bf16 v[64:79], v[248:251], v[140:143], v[64:79]
	ds_read_b128 v[240:243], v198 offset:17920
	s_waitcnt lgkmcnt(5)
	v_mfma_f32_32x32x16_bf16 v[48:63], v[152:155], v[144:147], v[48:63]
	ds_read_b128 v[244:247], v198 offset:13344
	s_waitcnt lgkmcnt(5)
	v_mfma_f32_32x32x16_bf16 v[64:79], v[156:159], v[144:147], v[64:79]
	ds_read_b128 v[248:251], v198 offset:17952
	s_waitcnt lgkmcnt(5)
	v_mfma_f32_32x32x16_bf16 v[48:63], v[160:163], v[148:151], v[48:63]
	ds_read_b128 v[152:155], v198 offset:13376
	s_waitcnt lgkmcnt(5)
	v_mfma_f32_32x32x16_bf16 v[64:79], v[164:167], v[148:151], v[64:79]
	ds_read_b128 v[156:159], v198 offset:17984
	s_nop 7
	v_max3_f32 v199, v48, v49, v50
	s_nop 1
	v_max3_f32 v252, v64, v65, v66
	v_max3_f32 v199, v199, v51, v52
	v_max3_f32 v252, v252, v67, v68
	v_max3_f32 v199, v199, v53, v54
	v_max3_f32 v252, v252, v69, v70
	v_max3_f32 v199, v199, v55, v56
	v_max3_f32 v252, v252, v71, v72
	v_max3_f32 v199, v199, v57, v58
	v_max3_f32 v252, v252, v73, v74
	v_max3_f32 v199, v199, v59, v60
	v_max3_f32 v252, v252, v75, v76
	v_max3_f32 v199, v199, v61, v62
	v_max3_f32 v252, v252, v77, v78
	v_max3_f32 v199, v199, v63, v79
	v_max_f32_e32 v199, v199, v252
	v_mov_b32_e32 v252, v199
	s_nop 1
	v_permlane32_swap_b32_e32 v199, v252
	v_max_f32_e32 v199, v199, v252
	s_cmp_eq_u32 s57, 0
	s_cbranch_scc1 .Lmla_rare0a
	v_cmp_lt_f32_e32 vcc, s51, v199
	s_cbranch_vccnz .Lmla_rare0a
.Lmla_back0a:
	v_exp_f32_e32 v48, v48
	v_exp_f32_e32 v49, v49
	v_exp_f32_e32 v50, v50
	v_add_f32_e32 v252, v48, v49
	v_exp_f32_e32 v51, v51
	v_add_f32_e32 v252, v252, v50
	v_exp_f32_e32 v52, v52
	v_add_f32_e32 v252, v252, v51
	v_exp_f32_e32 v53, v53
	v_add_f32_e32 v252, v252, v52
	v_exp_f32_e32 v54, v54
	v_add_f32_e32 v252, v252, v53
	v_exp_f32_e32 v55, v55
	v_add_f32_e32 v252, v252, v54
	v_add_f32_e32 v252, v252, v55
	v_cvt_pk_bf16_f32 v48, v48, v49
	v_cvt_pk_bf16_f32 v49, v50, v51
	v_cvt_pk_bf16_f32 v50, v52, v53
	v_cvt_pk_bf16_f32 v51, v54, v55
	v_exp_f32_e32 v56, v56
	v_exp_f32_e32 v57, v57
	v_exp_f32_e32 v58, v58
	v_add_f32_e32 v252, v252, v56
	v_exp_f32_e32 v59, v59
	v_add_f32_e32 v252, v252, v57
	v_exp_f32_e32 v60, v60
	v_add_f32_e32 v252, v252, v58
	v_exp_f32_e32 v61, v61
	v_add_f32_e32 v252, v252, v59
	v_exp_f32_e32 v62, v62
	v_add_f32_e32 v252, v252, v60
	v_exp_f32_e32 v63, v63
	v_add_f32_e32 v252, v252, v61
	v_add_f32_e32 v252, v252, v62
	v_add_f32_e32 v252, v252, v63
	v_cvt_pk_bf16_f32 v52, v56, v57
	v_cvt_pk_bf16_f32 v53, v58, v59
	v_cvt_pk_bf16_f32 v54, v60, v61
	v_cvt_pk_bf16_f32 v55, v62, v63
	v_exp_f32_e32 v64, v64
	v_exp_f32_e32 v65, v65
	v_exp_f32_e32 v66, v66
	v_add_f32_e32 v253, v64, v65
	v_exp_f32_e32 v67, v67
	v_add_f32_e32 v253, v253, v66
	v_exp_f32_e32 v68, v68
	v_add_f32_e32 v253, v253, v67
	v_exp_f32_e32 v69, v69
	v_add_f32_e32 v253, v253, v68
	v_exp_f32_e32 v70, v70
	v_add_f32_e32 v253, v253, v69
	v_exp_f32_e32 v71, v71
	v_add_f32_e32 v253, v253, v70
	v_add_f32_e32 v253, v253, v71
	v_cvt_pk_bf16_f32 v56, v64, v65
	v_cvt_pk_bf16_f32 v57, v66, v67
	v_cvt_pk_bf16_f32 v58, v68, v69
	v_cvt_pk_bf16_f32 v59, v70, v71
	v_exp_f32_e32 v72, v72
	v_exp_f32_e32 v73, v73
	v_exp_f32_e32 v74, v74
	v_add_f32_e32 v253, v253, v72
	v_exp_f32_e32 v75, v75
	v_add_f32_e32 v253, v253, v73
	v_exp_f32_e32 v76, v76
	v_add_f32_e32 v253, v253, v74
	v_exp_f32_e32 v77, v77
	v_add_f32_e32 v253, v253, v75
	v_exp_f32_e32 v78, v78
	v_add_f32_e32 v253, v253, v76
	v_exp_f32_e32 v79, v79
	v_add_f32_e32 v253, v253, v77
	v_add_f32_e32 v253, v253, v78
	v_add_f32_e32 v253, v253, v79
	v_cvt_pk_bf16_f32 v60, v72, v73
	v_cvt_pk_bf16_f32 v61, v74, v75
	v_cvt_pk_bf16_f32 v62, v76, v77
	v_cvt_pk_bf16_f32 v63, v78, v79
	v_add_f32_e32 v252, v252, v253
	v_add_f32_e32 v196, v196, v252
	s_waitcnt lgkmcnt(5)
	v_mfma_f32_32x32x16_bf16 v[16:31], v[236:239], v[48:51], v[16:31]
	ds_read_b128 v[160:163], v198 offset:13408
	s_waitcnt lgkmcnt(5)
	v_mfma_f32_32x32x16_bf16 v[0:15], v[240:243], v[48:51], v[0:15]
	ds_read_b128 v[164:167], v198 offset:18016
	s_waitcnt lgkmcnt(5)
	v_mfma_f32_32x32x16_bf16 v[16:31], v[244:247], v[52:55], v[16:31]
	ds_read_b128 v[236:239], v195 offset:22528
	s_waitcnt lgkmcnt(5)
	v_mfma_f32_32x32x16_bf16 v[0:15], v[248:251], v[52:55], v[0:15]
	ds_read_b128 v[240:243], v195 offset:29184
	s_waitcnt lgkmcnt(5)
	v_mfma_f32_32x32x16_bf16 v[16:31], v[152:155], v[56:59], v[16:31]
	ds_read_b128 v[244:247], v195 offset:22560
	s_waitcnt lgkmcnt(5)
; template <int DQK, int DV, int MODE, int QPRE, bool DIFF> ...
;     ...
;             if (!QKFIRST) {
;                 const LAS unsigned char* kb = lds + bi * BUF + l32 * KST + hi * 16;
;             {
;                 const bf16x8 a0 = *(const LAS bf16x8*)(kb), a1 = *(const LAS bf16x8*)(kb + 32 * KST);
;                 if (MODE == 1) { const f32x16 z16 = {0.f, 0.f, 0.f, 0.f, 0.f, 0.f, 0.f, 0.f, 0.f, 0.f, 0.f, 0.f, 0.f, 0.f, 0.f, 0.f};
;                     s0 = __builtin_amdgcn_mfma_f32_32x32x16_bf16(a0, qf[0], z16, 0, 0, 0); s1 = __builtin_amdgcn_mfma_f32_32x32x16_bf16(a1, qf[0], z16, 0, 0, 0); }
;                 else { s0 = __builtin_amdgcn_mfma_f32_32x32x16_bf16(a0, qf[0], negm, 0, 0, 0); s1 = __builtin_amdgcn_mfma_f32_32x32x16_bf16(a1, qf[0], negm, 0, 0, 0); }
;             }
; #pragma unroll
;             for (int d0 = 1; d0 < ND0; ++d0) {
;                 const bf16x8 a0 = *(const LAS bf16x8*)(kb + d0 * 32), a1 = *(const LAS bf16x8*)(kb + 32 * KST + d0 * 32);
;                 s0 = __builtin_amdgcn_mfma_f32_32x32x16_bf16(a0, qf[d0], s0, 0, 0, 0);
;                 s1 = __builtin_amdgcn_mfma_f32_32x32x16_bf16(a1, qf[d0], s1, 0, 0, 0);
;             }
;             }
;             bf16x8 vf[2][4];
;     ...
;             ATT_LOADV(vf[0], 0); if (!DEEP) ATT_LOADV(vf[1], 1);
;             __builtin_amdgcn_sched_barrier(0);
;             if (MODE != 1) {
;                 float mx = fmaxf(s0[0], s1[0]);
; #pragma unroll
;                 for (int r = 1; r < 16; ++r) mx = fmaxf(fmaxf(mx, s0[r]), s1[r]);
;                 { float a, b; swap32(mx, a, b); mx = fmaxf(a, b); }
;                 const bool first = (i == 0);
;                 if (first || __any(mx > 8.0f)) {
;                     const float dl = first ? mx : fmaxf(mx, 0.f);
;                     mhat += dl;
; #pragma unroll
;                     for (int r = 0; r < 16; ++r) { s0[r] -= dl; s1[r] -= dl; negm[r] = -mhat; }
;                     if (DEEP && QKFIRST && hf == 0 && (ATT_TILE(i0 + UNR - 1) <= my_last)) {
; #pragma unroll
;                         for (int r = 0; r < 16; ++r) { sq[UNR - 1][0][r] -= dl; sq[UNR - 1][1][r] -= dl; }
;                     }
;                     if (!first) {
;                         const float alpha = __builtin_amdgcn_exp2f(-dl);
;                         l_run *= alpha;
; #pragma unroll
;                         for (int i2 = 0; i2 < NDB; ++i2)
; #pragma unroll
	v_mfma_f32_32x32x16_bf16 v[0:15], v[156:159], v[56:59], v[0:15]
	ds_read_b128 v[248:251], v195 offset:29216
	s_waitcnt lgkmcnt(5)
	v_mfma_f32_32x32x16_bf16 v[16:31], v[160:163], v[60:63], v[16:31]
	ds_read_b128 v[152:155], v195 offset:22592
	s_waitcnt lgkmcnt(5)
	v_mfma_f32_32x32x16_bf16 v[0:15], v[164:167], v[60:63], v[0:15]
	ds_read_b128 v[156:159], v195 offset:29248
	s_waitcnt lgkmcnt(5)
	v_mfma_f32_32x32x16_bf16 v[204:219], v[236:239], v[128:131], v[32:47]
	ds_read_b128 v[160:163], v195 offset:22624
	s_waitcnt lgkmcnt(5)
	v_mfma_f32_32x32x16_bf16 v[220:235], v[240:243], v[128:131], v[32:47]
	ds_read_b128 v[164:167], v195 offset:29280
	s_waitcnt lgkmcnt(5)
	v_mfma_f32_32x32x16_bf16 v[204:219], v[244:247], v[132:135], v[204:219]
	ds_read_b128 v[236:239], v195 offset:22656
	s_waitcnt lgkmcnt(5)
	v_mfma_f32_32x32x16_bf16 v[220:235], v[248:251], v[132:135], v[220:235]
	ds_read_b128 v[240:243], v195 offset:29312
	s_waitcnt lgkmcnt(5)
	v_mfma_f32_32x32x16_bf16 v[204:219], v[152:155], v[136:139], v[204:219]
	ds_read_b128 v[244:247], v195 offset:22688
	s_waitcnt lgkmcnt(5)
	v_mfma_f32_32x32x16_bf16 v[220:235], v[156:159], v[136:139], v[220:235]
	ds_read_b128 v[248:251], v195 offset:29344
	s_waitcnt lgkmcnt(5)
	v_mfma_f32_32x32x16_bf16 v[204:219], v[160:163], v[140:143], v[204:219]
	ds_read_b128 v[152:155], v198 offset:35840
	s_waitcnt lgkmcnt(5)
	v_mfma_f32_32x32x16_bf16 v[220:235], v[164:167], v[140:143], v[220:235]
	ds_read_b128 v[156:159], v198 offset:40448
	s_waitcnt lgkmcnt(5)
	v_mfma_f32_32x32x16_bf16 v[204:219], v[236:239], v[144:147], v[204:219]
	ds_read_b128 v[160:163], v198 offset:35872
	s_waitcnt lgkmcnt(5)
	v_mfma_f32_32x32x16_bf16 v[220:235], v[240:243], v[144:147], v[220:235]
	ds_read_b128 v[164:167], v198 offset:40480
	s_waitcnt lgkmcnt(5)
	v_mfma_f32_32x32x16_bf16 v[204:219], v[244:247], v[148:151], v[204:219]
	ds_read_b128 v[236:239], v198 offset:35904
	s_waitcnt lgkmcnt(5)
	v_mfma_f32_32x32x16_bf16 v[220:235], v[248:251], v[148:151], v[220:235]
	ds_read_b128 v[240:243], v198 offset:40512
	s_nop 7
	v_max3_f32 v199, v204, v205, v206
	s_nop 1
	v_max3_f32 v252, v220, v221, v222
	v_max3_f32 v199, v199, v207, v208
	v_max3_f32 v252, v252, v223, v224
	v_max3_f32 v199, v199, v209, v210
	v_max3_f32 v252, v252, v225, v226
	v_max3_f32 v199, v199, v211, v212
	v_max3_f32 v252, v252, v227, v228
	v_max3_f32 v199, v199, v213, v214
	v_max3_f32 v252, v252, v229, v230
	v_max3_f32 v199, v199, v215, v216
	v_max3_f32 v252, v252, v231, v232
	v_max3_f32 v199, v199, v217, v218
	v_max3_f32 v252, v252, v233, v234
	v_max3_f32 v199, v199, v219, v235
	v_max_f32_e32 v199, v199, v252
	v_mov_b32_e32 v252, v199
	s_nop 1
	v_permlane32_swap_b32_e32 v199, v252
	v_max_f32_e32 v199, v199, v252
	v_cmp_lt_f32_e32 vcc, s51, v199
	s_cbranch_vccnz .Lmla_rare0b
.Lmla_back0b:
	v_exp_f32_e32 v204, v204
	v_exp_f32_e32 v205, v205
	v_exp_f32_e32 v206, v206
	v_add_f32_e32 v252, v204, v205
	v_exp_f32_e32 v207, v207
	v_add_f32_e32 v252, v252, v206
	v_exp_f32_e32 v208, v208
	v_add_f32_e32 v252, v252, v207
	v_exp_f32_e32 v209, v209
	v_add_f32_e32 v252, v252, v208
	v_exp_f32_e32 v210, v210
	v_add_f32_e32 v252, v252, v209
	v_exp_f32_e32 v211, v211
	v_add_f32_e32 v252, v252, v210
	v_add_f32_e32 v252, v252, v211
	v_cvt_pk_bf16_f32 v204, v204, v205
	v_cvt_pk_bf16_f32 v205, v206, v207
	v_cvt_pk_bf16_f32 v206, v208, v209
	v_cvt_pk_bf16_f32 v207, v210, v211
	v_exp_f32_e32 v212, v212
	v_exp_f32_e32 v213, v213
	v_exp_f32_e32 v214, v214
	v_add_f32_e32 v252, v252, v212
	v_exp_f32_e32 v215, v215
	v_add_f32_e32 v252, v252, v213
	v_exp_f32_e32 v216, v216
	v_add_f32_e32 v252, v252, v214
	v_exp_f32_e32 v217, v217
	v_add_f32_e32 v252, v252, v215
	v_exp_f32_e32 v218, v218
	v_add_f32_e32 v252, v252, v216
	v_exp_f32_e32 v219, v219
	v_add_f32_e32 v252, v252, v217
	v_add_f32_e32 v252, v252, v218
	v_add_f32_e32 v252, v252, v219
	v_cvt_pk_bf16_f32 v208, v212, v213
	v_cvt_pk_bf16_f32 v209, v214, v215
	v_cvt_pk_bf16_f32 v210, v216, v217
	v_cvt_pk_bf16_f32 v211, v218, v219
	v_exp_f32_e32 v220, v220
	v_exp_f32_e32 v221, v221
	v_exp_f32_e32 v222, v222
	v_add_f32_e32 v253, v220, v221
	v_exp_f32_e32 v223, v223
	v_add_f32_e32 v253, v253, v222
	v_exp_f32_e32 v224, v224
	v_add_f32_e32 v253, v253, v223
	v_exp_f32_e32 v225, v225
	v_add_f32_e32 v253, v253, v224
	v_exp_f32_e32 v226, v226
	v_add_f32_e32 v253, v253, v225
	v_exp_f32_e32 v227, v227
	v_add_f32_e32 v253, v253, v226
	v_add_f32_e32 v253, v253, v227
	v_cvt_pk_bf16_f32 v212, v220, v221
	v_cvt_pk_bf16_f32 v213, v222, v223
	v_cvt_pk_bf16_f32 v214, v224, v225
	v_cvt_pk_bf16_f32 v215, v226, v227
	v_exp_f32_e32 v228, v228
	v_exp_f32_e32 v229, v229
	v_exp_f32_e32 v230, v230
	v_add_f32_e32 v253, v253, v228
	v_exp_f32_e32 v231, v231
	v_add_f32_e32 v253, v253, v229
	v_exp_f32_e32 v232, v232
	v_add_f32_e32 v253, v253, v230
	v_exp_f32_e32 v233, v233
	v_add_f32_e32 v253, v253, v231
	v_exp_f32_e32 v234, v234
	v_add_f32_e32 v253, v253, v232
	v_exp_f32_e32 v235, v235
	v_add_f32_e32 v253, v253, v233
	v_add_f32_e32 v253, v253, v234
	v_add_f32_e32 v253, v253, v235
	v_cvt_pk_bf16_f32 v216, v228, v229
	v_cvt_pk_bf16_f32 v217, v230, v231
	v_cvt_pk_bf16_f32 v218, v232, v233
	v_cvt_pk_bf16_f32 v219, v234, v235
	v_add_f32_e32 v252, v252, v253
	v_add_f32_e32 v196, v196, v252
	s_waitcnt lgkmcnt(5)
	v_mfma_f32_32x32x16_bf16 v[16:31], v[152:155], v[204:207], v[16:31]
	ds_read_b128 v[244:247], v198 offset:35936
	s_waitcnt lgkmcnt(5)
	v_mfma_f32_32x32x16_bf16 v[0:15], v[156:159], v[204:207], v[0:15]
	ds_read_b128 v[248:251], v198 offset:40544
	s_waitcnt lgkmcnt(5)
	v_mfma_f32_32x32x16_bf16 v[16:31], v[160:163], v[208:211], v[16:31]
	s_waitcnt lgkmcnt(4)
	v_mfma_f32_32x32x16_bf16 v[0:15], v[164:167], v[208:211], v[0:15]
	s_waitcnt lgkmcnt(3)
	v_mfma_f32_32x32x16_bf16 v[16:31], v[236:239], v[212:215], v[16:31]
	s_waitcnt lgkmcnt(2)
	v_mfma_f32_32x32x16_bf16 v[0:15], v[240:243], v[212:215], v[0:15]
	s_waitcnt lgkmcnt(1)
	v_mfma_f32_32x32x16_bf16 v[16:31], v[244:247], v[216:219], v[16:31]
	s_waitcnt lgkmcnt(0)
	v_mfma_f32_32x32x16_bf16 v[0:15], v[248:251], v[216:219], v[0:15]
	s_branch .LBB0_1667

; template <int DQK, int DV, int MODE, int QPRE, bool DIFF> ...
;     ...
;             if (!QKFIRST) {
;                 const LAS unsigned char* kb = lds + bi * BUF + l32 * KST + hi * 16;
;             {
;                 const bf16x8 a0 = *(const LAS bf16x8*)(kb), a1 = *(const LAS bf16x8*)(kb + 32 * KST);
;                 if (MODE == 1) { const f32x16 z16 = {0.f, 0.f, 0.f, 0.f, 0.f, 0.f, 0.f, 0.f, 0.f, 0.f, 0.f, 0.f, 0.f, 0.f, 0.f, 0.f};
;                     s0 = __builtin_amdgcn_mfma_f32_32x32x16_bf16(a0, qf[0], z16, 0, 0, 0); s1 = __builtin_amdgcn_mfma_f32_32x32x16_bf16(a1, qf[0], z16, 0, 0, 0); }
;                 else { s0 = __builtin_amdgcn_mfma_f32_32x32x16_bf16(a0, qf[0], negm, 0, 0, 0); s1 = __builtin_amdgcn_mfma_f32_32x32x16_bf16(a1, qf[0], negm, 0, 0, 0); }
;             }
; #pragma unroll
;             for (int d0 = 1; d0 < ND0; ++d0) {
;                 const bf16x8 a0 = *(const LAS bf16x8*)(kb + d0 * 32), a1 = *(const LAS bf16x8*)(kb + 32 * KST + d0 * 32);
;                 s0 = __builtin_amdgcn_mfma_f32_32x32x16_bf16(a0, qf[d0], s0, 0, 0, 0);
;                 s1 = __builtin_amdgcn_mfma_f32_32x32x16_bf16(a1, qf[d0], s1, 0, 0, 0);
;             }
;             }
;             bf16x8 vf[2][4];
;     ...
;             ATT_LOADV(vf[0], 0); if (!DEEP) ATT_LOADV(vf[1], 1);
;             __builtin_amdgcn_sched_barrier(0);
;             if (MODE != 1) {
;                 float mx = fmaxf(s0[0], s1[0]);
; #pragma unroll
;                 for (int r = 1; r < 16; ++r) mx = fmaxf(fmaxf(mx, s0[r]), s1[r]);
;                 { float a, b; swap32(mx, a, b); mx = fmaxf(a, b); }
;                 const bool first = (i == 0);
;                 if (first || __any(mx > 8.0f)) {
;                     const float dl = first ? mx : fmaxf(mx, 0.f);
;                     mhat += dl;
; #pragma unroll
;                     for (int r = 0; r < 16; ++r) { s0[r] -= dl; s1[r] -= dl; negm[r] = -mhat; }
;                     if (DEEP && QKFIRST && hf == 0 && (ATT_TILE(i0 + UNR - 1) <= my_last)) {
; #pragma unroll
;                         for (int r = 0; r < 16; ++r) { sq[UNR - 1][0][r] -= dl; sq[UNR - 1][1][r] -= dl; }
;                     }
;                     if (!first) {
;                         const float alpha = __builtin_amdgcn_exp2f(-dl);
;                         l_run *= alpha;
; #pragma unroll
;                         for (int i2 = 0; i2 < NDB; ++i2)
; #pragma unroll
.Lmla_pair1:
	ds_read_b128 v[152:155], v195 offset:45056
	ds_read_b128 v[156:159], v195 offset:51712
	ds_read_b128 v[160:163], v195 offset:45088
	ds_read_b128 v[164:167], v195 offset:51744
	ds_read_b128 v[236:239], v195 offset:45120
	ds_read_b128 v[240:243], v195 offset:51776
	s_waitcnt lgkmcnt(5)
	v_mfma_f32_32x32x16_bf16 v[48:63], v[152:155], v[128:131], v[32:47]
	ds_read_b128 v[244:247], v195 offset:45152
	s_waitcnt lgkmcnt(5)
	v_mfma_f32_32x32x16_bf16 v[64:79], v[156:159], v[128:131], v[32:47]
	ds_read_b128 v[248:251], v195 offset:51808
	s_waitcnt lgkmcnt(5)
	v_mfma_f32_32x32x16_bf16 v[48:63], v[160:163], v[132:135], v[48:63]
	ds_read_b128 v[152:155], v195 offset:45184
	s_waitcnt lgkmcnt(5)
	v_mfma_f32_32x32x16_bf16 v[64:79], v[164:167], v[132:135], v[64:79]
	ds_read_b128 v[156:159], v195 offset:51840
	s_waitcnt lgkmcnt(5)
	v_mfma_f32_32x32x16_bf16 v[48:63], v[236:239], v[136:139], v[48:63]
	ds_read_b128 v[160:163], v195 offset:45216
	s_waitcnt lgkmcnt(5)
	v_mfma_f32_32x32x16_bf16 v[64:79], v[240:243], v[136:139], v[64:79]
	ds_read_b128 v[164:167], v195 offset:51872
	s_waitcnt lgkmcnt(5)
	v_mfma_f32_32x32x16_bf16 v[48:63], v[244:247], v[140:143], v[48:63]
	ds_read_b128 v[236:239], v198 offset:58368
	s_waitcnt lgkmcnt(5)
	v_mfma_f32_32x32x16_bf16 v[64:79], v[248:251], v[140:143], v[64:79]
	ds_read_b128 v[240:243], v198 offset:62976
	s_waitcnt lgkmcnt(5)
	v_mfma_f32_32x32x16_bf16 v[48:63], v[152:155], v[144:147], v[48:63]
	ds_read_b128 v[244:247], v198 offset:58400
	s_waitcnt lgkmcnt(5)
	v_mfma_f32_32x32x16_bf16 v[64:79], v[156:159], v[144:147], v[64:79]
	ds_read_b128 v[248:251], v198 offset:63008
	s_waitcnt lgkmcnt(5)
	v_mfma_f32_32x32x16_bf16 v[48:63], v[160:163], v[148:151], v[48:63]
	ds_read_b128 v[152:155], v198 offset:58432
	s_waitcnt lgkmcnt(5)
	v_mfma_f32_32x32x16_bf16 v[64:79], v[164:167], v[148:151], v[64:79]
	ds_read_b128 v[156:159], v198 offset:63040
	s_nop 7
	v_max3_f32 v199, v48, v49, v50
	s_nop 1
	v_max3_f32 v252, v64, v65, v66
	v_max3_f32 v199, v199, v51, v52
	v_max3_f32 v252, v252, v67, v68
	v_max3_f32 v199, v199, v53, v54
	v_max3_f32 v252, v252, v69, v70
	v_max3_f32 v199, v199, v55, v56
	v_max3_f32 v252, v252, v71, v72
	v_max3_f32 v199, v199, v57, v58
	v_max3_f32 v252, v252, v73, v74
	v_max3_f32 v199, v199, v59, v60
	v_max3_f32 v252, v252, v75, v76
	v_max3_f32 v199, v199, v61, v62
	v_max3_f32 v252, v252, v77, v78
	v_max3_f32 v199, v199, v63, v79
	v_max_f32_e32 v199, v199, v252
	v_mov_b32_e32 v252, v199
	s_nop 1
	v_permlane32_swap_b32_e32 v199, v252
	v_max_f32_e32 v199, v199, v252
	v_cmp_lt_f32_e32 vcc, s51, v199
	s_cbranch_vccnz .Lmla_rare1a
.Lmla_back1a:
	v_exp_f32_e32 v48, v48
	v_exp_f32_e32 v49, v49
	v_exp_f32_e32 v50, v50
	v_add_f32_e32 v252, v48, v49
	v_exp_f32_e32 v51, v51
	v_add_f32_e32 v252, v252, v50
	v_exp_f32_e32 v52, v52
	v_add_f32_e32 v252, v252, v51
	v_exp_f32_e32 v53, v53
	v_add_f32_e32 v252, v252, v52
	v_exp_f32_e32 v54, v54
	v_add_f32_e32 v252, v252, v53
	v_exp_f32_e32 v55, v55
	v_add_f32_e32 v252, v252, v54
	v_add_f32_e32 v252, v252, v55
	v_cvt_pk_bf16_f32 v48, v48, v49
	v_cvt_pk_bf16_f32 v49, v50, v51
	v_cvt_pk_bf16_f32 v50, v52, v53
	v_cvt_pk_bf16_f32 v51, v54, v55
	v_exp_f32_e32 v56, v56
	v_exp_f32_e32 v57, v57
	v_exp_f32_e32 v58, v58
	v_add_f32_e32 v252, v252, v56
	v_exp_f32_e32 v59, v59
	v_add_f32_e32 v252, v252, v57
	v_exp_f32_e32 v60, v60
	v_add_f32_e32 v252, v252, v58
	v_exp_f32_e32 v61, v61
	v_add_f32_e32 v252, v252, v59
	v_exp_f32_e32 v62, v62
	v_add_f32_e32 v252, v252, v60
	v_exp_f32_e32 v63, v63
	v_add_f32_e32 v252, v252, v61
	v_add_f32_e32 v252, v252, v62
	v_add_f32_e32 v252, v252, v63
	v_cvt_pk_bf16_f32 v52, v56, v57
	v_cvt_pk_bf16_f32 v53, v58, v59
	v_cvt_pk_bf16_f32 v54, v60, v61
	v_cvt_pk_bf16_f32 v55, v62, v63
	v_exp_f32_e32 v64, v64
	v_exp_f32_e32 v65, v65
	v_exp_f32_e32 v66, v66
	v_add_f32_e32 v253, v64, v65
	v_exp_f32_e32 v67, v67
	v_add_f32_e32 v253, v253, v66
	v_exp_f32_e32 v68, v68
	v_add_f32_e32 v253, v253, v67
	v_exp_f32_e32 v69, v69
	v_add_f32_e32 v253, v253, v68
	v_exp_f32_e32 v70, v70
	v_add_f32_e32 v253, v253, v69
	v_exp_f32_e32 v71, v71
	v_add_f32_e32 v253, v253, v70
	v_add_f32_e32 v253, v253, v71
	v_cvt_pk_bf16_f32 v56, v64, v65
	v_cvt_pk_bf16_f32 v57, v66, v67
	v_cvt_pk_bf16_f32 v58, v68, v69
	v_cvt_pk_bf16_f32 v59, v70, v71
	v_exp_f32_e32 v72, v72
	v_exp_f32_e32 v73, v73
	v_exp_f32_e32 v74, v74
	v_add_f32_e32 v253, v253, v72
	v_exp_f32_e32 v75, v75
	v_add_f32_e32 v253, v253, v73
	v_exp_f32_e32 v76, v76
	v_add_f32_e32 v253, v253, v74
	v_exp_f32_e32 v77, v77
	v_add_f32_e32 v253, v253, v75
	v_exp_f32_e32 v78, v78
	v_add_f32_e32 v253, v253, v76
	v_exp_f32_e32 v79, v79
	v_add_f32_e32 v253, v253, v77
	v_add_f32_e32 v253, v253, v78
	v_add_f32_e32 v253, v253, v79
	v_cvt_pk_bf16_f32 v60, v72, v73
	v_cvt_pk_bf16_f32 v61, v74, v75
	v_cvt_pk_bf16_f32 v62, v76, v77
	v_cvt_pk_bf16_f32 v63, v78, v79
	v_add_f32_e32 v252, v252, v253
	v_add_f32_e32 v196, v196, v252
	s_waitcnt lgkmcnt(5)
	v_mfma_f32_32x32x16_bf16 v[16:31], v[236:239], v[48:51], v[16:31]
	ds_read_b128 v[160:163], v198 offset:58464
	s_waitcnt lgkmcnt(5)
	v_mfma_f32_32x32x16_bf16 v[0:15], v[240:243], v[48:51], v[0:15]
	ds_read_b128 v[164:167], v198 offset:63072
	s_waitcnt lgkmcnt(5)
	v_mfma_f32_32x32x16_bf16 v[16:31], v[244:247], v[52:55], v[16:31]
	ds_read_b128 v[236:239], v194
	s_waitcnt lgkmcnt(5)
	v_mfma_f32_32x32x16_bf16 v[0:15], v[248:251], v[52:55], v[0:15]
	ds_read_b128 v[240:243], v194 offset:6656
	s_waitcnt lgkmcnt(5)
	v_mfma_f32_32x32x16_bf16 v[16:31], v[152:155], v[56:59], v[16:31]
	ds_read_b128 v[244:247], v194 offset:32
	s_waitcnt lgkmcnt(5)
; template <int DQK, int DV, int MODE, int QPRE, bool DIFF> ...
;     ...
;             if (!QKFIRST) {
;                 const LAS unsigned char* kb = lds + bi * BUF + l32 * KST + hi * 16;
;             {
;                 const bf16x8 a0 = *(const LAS bf16x8*)(kb), a1 = *(const LAS bf16x8*)(kb + 32 * KST);
;                 if (MODE == 1) { const f32x16 z16 = {0.f, 0.f, 0.f, 0.f, 0.f, 0.f, 0.f, 0.f, 0.f, 0.f, 0.f, 0.f, 0.f, 0.f, 0.f, 0.f};
;                     s0 = __builtin_amdgcn_mfma_f32_32x32x16_bf16(a0, qf[0], z16, 0, 0, 0); s1 = __builtin_amdgcn_mfma_f32_32x32x16_bf16(a1, qf[0], z16, 0, 0, 0); }
;                 else { s0 = __builtin_amdgcn_mfma_f32_32x32x16_bf16(a0, qf[0], negm, 0, 0, 0); s1 = __builtin_amdgcn_mfma_f32_32x32x16_bf16(a1, qf[0], negm, 0, 0, 0); }
;             }
; #pragma unroll
;             for (int d0 = 1; d0 < ND0; ++d0) {
;                 const bf16x8 a0 = *(const LAS bf16x8*)(kb + d0 * 32), a1 = *(const LAS bf16x8*)(kb + 32 * KST + d0 * 32);
;                 s0 = __builtin_amdgcn_mfma_f32_32x32x16_bf16(a0, qf[d0], s0, 0, 0, 0);
;                 s1 = __builtin_amdgcn_mfma_f32_32x32x16_bf16(a1, qf[d0], s1, 0, 0, 0);
;             }
;             }
;             bf16x8 vf[2][4];
;     ...
;             ATT_LOADV(vf[0], 0); if (!DEEP) ATT_LOADV(vf[1], 1);
;             __builtin_amdgcn_sched_barrier(0);
;             if (MODE != 1) {
;                 float mx = fmaxf(s0[0], s1[0]);
; #pragma unroll
;                 for (int r = 1; r < 16; ++r) mx = fmaxf(fmaxf(mx, s0[r]), s1[r]);
;                 { float a, b; swap32(mx, a, b); mx = fmaxf(a, b); }
;                 const bool first = (i == 0);
;                 if (first || __any(mx > 8.0f)) {
;                     const float dl = first ? mx : fmaxf(mx, 0.f);
;                     mhat += dl;
; #pragma unroll
;                     for (int r = 0; r < 16; ++r) { s0[r] -= dl; s1[r] -= dl; negm[r] = -mhat; }
;                     if (DEEP && QKFIRST && hf == 0 && (ATT_TILE(i0 + UNR - 1) <= my_last)) {
; #pragma unroll
;                         for (int r = 0; r < 16; ++r) { sq[UNR - 1][0][r] -= dl; sq[UNR - 1][1][r] -= dl; }
;                     }
;                     if (!first) {
;                         const float alpha = __builtin_amdgcn_exp2f(-dl);
;                         l_run *= alpha;
; #pragma unroll
;                         for (int i2 = 0; i2 < NDB; ++i2)
; #pragma unroll
	v_mfma_f32_32x32x16_bf16 v[0:15], v[156:159], v[56:59], v[0:15]
	ds_read_b128 v[248:251], v194 offset:6688
	s_waitcnt lgkmcnt(5)
	v_mfma_f32_32x32x16_bf16 v[16:31], v[160:163], v[60:63], v[16:31]
	ds_read_b128 v[152:155], v194 offset:64
	s_waitcnt lgkmcnt(5)
	v_mfma_f32_32x32x16_bf16 v[0:15], v[164:167], v[60:63], v[0:15]
	ds_read_b128 v[156:159], v194 offset:6720
	s_waitcnt lgkmcnt(5)
	v_mfma_f32_32x32x16_bf16 v[204:219], v[236:239], v[128:131], v[32:47]
	ds_read_b128 v[160:163], v194 offset:96
	s_waitcnt lgkmcnt(5)
	v_mfma_f32_32x32x16_bf16 v[220:235], v[240:243], v[128:131], v[32:47]
	ds_read_b128 v[164:167], v194 offset:6752
	s_waitcnt lgkmcnt(5)
	v_mfma_f32_32x32x16_bf16 v[204:219], v[244:247], v[132:135], v[204:219]
	ds_read_b128 v[236:239], v194 offset:128
	s_waitcnt lgkmcnt(5)
	v_mfma_f32_32x32x16_bf16 v[220:235], v[248:251], v[132:135], v[220:235]
	ds_read_b128 v[240:243], v194 offset:6784
	s_waitcnt lgkmcnt(5)
	v_mfma_f32_32x32x16_bf16 v[204:219], v[152:155], v[136:139], v[204:219]
	ds_read_b128 v[244:247], v194 offset:160
	s_waitcnt lgkmcnt(5)
	v_mfma_f32_32x32x16_bf16 v[220:235], v[156:159], v[136:139], v[220:235]
	ds_read_b128 v[248:251], v194 offset:6816
	s_waitcnt lgkmcnt(5)
	v_mfma_f32_32x32x16_bf16 v[204:219], v[160:163], v[140:143], v[204:219]
	ds_read_b128 v[152:155], v197
	s_waitcnt lgkmcnt(5)
	v_mfma_f32_32x32x16_bf16 v[220:235], v[164:167], v[140:143], v[220:235]
	ds_read_b128 v[156:159], v197 offset:4608
	s_waitcnt lgkmcnt(5)
	v_mfma_f32_32x32x16_bf16 v[204:219], v[236:239], v[144:147], v[204:219]
	ds_read_b128 v[160:163], v197 offset:32
	s_waitcnt lgkmcnt(5)
	v_mfma_f32_32x32x16_bf16 v[220:235], v[240:243], v[144:147], v[220:235]
	ds_read_b128 v[164:167], v197 offset:4640
	s_waitcnt lgkmcnt(5)
	v_mfma_f32_32x32x16_bf16 v[204:219], v[244:247], v[148:151], v[204:219]
	ds_read_b128 v[236:239], v197 offset:64
	s_waitcnt lgkmcnt(5)
	v_mfma_f32_32x32x16_bf16 v[220:235], v[248:251], v[148:151], v[220:235]
	ds_read_b128 v[240:243], v197 offset:4672
	s_nop 7
	v_max3_f32 v199, v204, v205, v206
	s_nop 1
	v_max3_f32 v252, v220, v221, v222
	v_max3_f32 v199, v199, v207, v208
	v_max3_f32 v252, v252, v223, v224
	v_max3_f32 v199, v199, v209, v210
	v_max3_f32 v252, v252, v225, v226
	v_max3_f32 v199, v199, v211, v212
	v_max3_f32 v252, v252, v227, v228
	v_max3_f32 v199, v199, v213, v214
	v_max3_f32 v252, v252, v229, v230
	v_max3_f32 v199, v199, v215, v216
	v_max3_f32 v252, v252, v231, v232
	v_max3_f32 v199, v199, v217, v218
	v_max3_f32 v252, v252, v233, v234
	v_max3_f32 v199, v199, v219, v235
	v_max_f32_e32 v199, v199, v252
	v_mov_b32_e32 v252, v199
	s_nop 1
	v_permlane32_swap_b32_e32 v199, v252
	v_max_f32_e32 v199, v199, v252
	v_cmp_lt_f32_e32 vcc, s51, v199
	s_cbranch_vccnz .Lmla_rare1b
.Lmla_back1b:
	v_exp_f32_e32 v204, v204
	v_exp_f32_e32 v205, v205
	v_exp_f32_e32 v206, v206
	v_add_f32_e32 v252, v204, v205
	v_exp_f32_e32 v207, v207
	v_add_f32_e32 v252, v252, v206
	v_exp_f32_e32 v208, v208
	v_add_f32_e32 v252, v252, v207
	v_exp_f32_e32 v209, v209
	v_add_f32_e32 v252, v252, v208
	v_exp_f32_e32 v210, v210
	v_add_f32_e32 v252, v252, v209
	v_exp_f32_e32 v211, v211
	v_add_f32_e32 v252, v252, v210
	v_add_f32_e32 v252, v252, v211
	v_cvt_pk_bf16_f32 v204, v204, v205
	v_cvt_pk_bf16_f32 v205, v206, v207
	v_cvt_pk_bf16_f32 v206, v208, v209
	v_cvt_pk_bf16_f32 v207, v210, v211
	v_exp_f32_e32 v212, v212
	v_exp_f32_e32 v213, v213
	v_exp_f32_e32 v214, v214
	v_add_f32_e32 v252, v252, v212
	v_exp_f32_e32 v215, v215
	v_add_f32_e32 v252, v252, v213
	v_exp_f32_e32 v216, v216
	v_add_f32_e32 v252, v252, v214
	v_exp_f32_e32 v217, v217
	v_add_f32_e32 v252, v252, v215
	v_exp_f32_e32 v218, v218
	v_add_f32_e32 v252, v252, v216
	v_exp_f32_e32 v219, v219
	v_add_f32_e32 v252, v252, v217
	v_add_f32_e32 v252, v252, v218
	v_add_f32_e32 v252, v252, v219
	v_cvt_pk_bf16_f32 v208, v212, v213
	v_cvt_pk_bf16_f32 v209, v214, v215
	v_cvt_pk_bf16_f32 v210, v216, v217
	v_cvt_pk_bf16_f32 v211, v218, v219
	v_exp_f32_e32 v220, v220
	v_exp_f32_e32 v221, v221
	v_exp_f32_e32 v222, v222
	v_add_f32_e32 v253, v220, v221
	v_exp_f32_e32 v223, v223
	v_add_f32_e32 v253, v253, v222
	v_exp_f32_e32 v224, v224
	v_add_f32_e32 v253, v253, v223
	v_exp_f32_e32 v225, v225
	v_add_f32_e32 v253, v253, v224
	v_exp_f32_e32 v226, v226
	v_add_f32_e32 v253, v253, v225
	v_exp_f32_e32 v227, v227
	v_add_f32_e32 v253, v253, v226
	v_add_f32_e32 v253, v253, v227
	v_cvt_pk_bf16_f32 v212, v220, v221
	v_cvt_pk_bf16_f32 v213, v222, v223
	v_cvt_pk_bf16_f32 v214, v224, v225
	v_cvt_pk_bf16_f32 v215, v226, v227
	v_exp_f32_e32 v228, v228
	v_exp_f32_e32 v229, v229
	v_exp_f32_e32 v230, v230
	v_add_f32_e32 v253, v253, v228
	v_exp_f32_e32 v231, v231
	v_add_f32_e32 v253, v253, v229
	v_exp_f32_e32 v232, v232
	v_add_f32_e32 v253, v253, v230
	v_exp_f32_e32 v233, v233
	v_add_f32_e32 v253, v253, v231
	v_exp_f32_e32 v234, v234
	v_add_f32_e32 v253, v253, v232
	v_exp_f32_e32 v235, v235
	v_add_f32_e32 v253, v253, v233
	v_add_f32_e32 v253, v253, v234
	v_add_f32_e32 v253, v253, v235
	v_cvt_pk_bf16_f32 v216, v228, v229
	v_cvt_pk_bf16_f32 v217, v230, v231
	v_cvt_pk_bf16_f32 v218, v232, v233
	v_cvt_pk_bf16_f32 v219, v234, v235
	v_add_f32_e32 v252, v252, v253
	v_add_f32_e32 v196, v196, v252
	s_waitcnt lgkmcnt(5)
	v_mfma_f32_32x32x16_bf16 v[16:31], v[152:155], v[204:207], v[16:31]
	ds_read_b128 v[244:247], v197 offset:96
	s_waitcnt lgkmcnt(5)
	v_mfma_f32_32x32x16_bf16 v[0:15], v[156:159], v[204:207], v[0:15]
	ds_read_b128 v[248:251], v197 offset:4704
	s_waitcnt lgkmcnt(5)
	v_mfma_f32_32x32x16_bf16 v[16:31], v[160:163], v[208:211], v[16:31]
	s_waitcnt lgkmcnt(4)
	v_mfma_f32_32x32x16_bf16 v[0:15], v[164:167], v[208:211], v[0:15]
	s_waitcnt lgkmcnt(3)
	v_mfma_f32_32x32x16_bf16 v[16:31], v[236:239], v[212:215], v[16:31]
	s_waitcnt lgkmcnt(2)
	v_mfma_f32_32x32x16_bf16 v[0:15], v[240:243], v[212:215], v[0:15]
	s_waitcnt lgkmcnt(1)
	v_mfma_f32_32x32x16_bf16 v[16:31], v[244:247], v[216:219], v[16:31]
	s_waitcnt lgkmcnt(0)
	v_mfma_f32_32x32x16_bf16 v[0:15], v[248:251], v[216:219], v[0:15]
	s_branch .LBB0_1701
